# attention items assigned XCD-major on the 256-workgroup grid (32 consecutive items, whose K/V windows overlap by half, per XCD) so shared K/V rows hit one L2
# speedup vs baseline: 1.0048x; 1.0048x over previous
;     __device__ __forceinline__ bf16_t* bfp(size_t off) const { return (bf16_t*)(ws + off); }
; __device__ __forceinline__ void attn_fetch(const Ctx& C, int it, u32x4 (&kv)[4], u32x4 (&vv)[4], u32x4 (&qv)[2]) {
;     const int tid = C.tid;
;     const int b = it / 384, rem = it % 384, hq = rem >> 5, kk = rem & 31, g = hq >> 2, dil = 1 << (2 * g), n = SEQ / dil, nblk = 32 / dil, r = kk / nblk, jb = kk % nblk;
;     const bf16_t* pd = C.bfp(OFF_PROJD);
; #pragma unroll
;     for (int k = 0; k < 4; ++k) { const int id = tid + NTHR * k, cidx = id >> 3, ch = id & 7, ik = 128 * jb - 64 + cidx;
;         kv[k] = (u32x4){0u, 0u, 0u, 0u}; vv[k] = (u32x4){0u, 0u, 0u, 0u};
;         if (ik >= 0 && ik < n) { const bf16_t* row = pd + (size_t)(b * SEQ + r + dil * ik) * 2304; kv[k] = *(const u32x4*)(row + 768 + hq * 64 + ch * 8); vv[k] = *(const u32x4*)(row + 1536 + hq * 64 + ch * 8); } }
; __global__ void __launch_bounds__(NTHR, 2) fwd_megakernel(Params prm) {
;     ...
;         { u32x4 akv[4], avv[4], aqv[2]; attn_fetch(C, bid, akv, avv, aqv);
;           for (int it = bid; it < 3072; it += G) attn_item(C, it, it + G, akv, avv, aqv); }
.LBB0_5:
	s_or_b64 exec, exec, s[2:3]
	s_lshl_b32 s18, s26, 3
	s_lshl_b32 s11, s90, 3
	s_ashr_i32 s19, s18, 31
	s_lshl_b32 s20, s26, 4
	s_add_u32 s2, s24, 0x1eb00200
	s_addc_u32 s3, s25, 0
	v_writelane_b32 v252, s2, 4
	s_mov_b32 s37, 0
	v_mov_b32_e32 v65, 0
	v_writelane_b32 v252, s3, 5
	s_add_u32 s2, s24, 0x1eb00400
	s_addc_u32 s3, s25, 0
	v_writelane_b32 v252, s2, 6
	v_mov_b32_e32 v216, 1
	v_mov_b32_e32 v217, 0x3c0881c4
	v_writelane_b32 v252, s3, 7
	s_add_u32 s2, s24, 0x1eb00500
	s_addc_u32 s3, s25, 0
	v_writelane_b32 v252, s2, 8
	v_mov_b32_e32 v218, 0xbab64f3b
	v_mov_b32_e32 v219, 0x3ecc95a3
	v_writelane_b32 v252, s3, 9
	s_add_u32 s2, s24, 0x1eb00600
	s_addc_u32 s3, s25, 0
	v_writelane_b32 v252, s2, 10
	v_mov_b32_e32 v220, 0x260
	v_mov_b32_e32 v238, 0x358637bd
	v_writelane_b32 v252, s3, 11
	s_add_u32 s2, s24, 0x1eb00700
	s_addc_u32 s3, s25, 0
	v_writelane_b32 v252, s2, 12
	v_mov_b32_e32 v222, 0x7fc00000
	v_mov_b32_e32 v225, 0x41b17218
	v_writelane_b32 v252, s3, 13
	s_add_u32 s2, s24, 0x1eb00800
	s_addc_u32 s3, s25, 0
	v_writelane_b32 v252, s2, 14
	v_mov_b32_e32 v182, 0x3f317218
	v_mov_b32_e32 v226, 0x7f800000
	v_writelane_b32 v252, s3, 15
	s_add_u32 s2, s24, 0x1eb00900
	s_addc_u32 s3, s25, 0
	v_writelane_b32 v252, s2, 16
	v_mov_b32_e32 v227, 0xff800000
	v_mov_b64_e32 v[184:185], 0x1ff
	v_writelane_b32 v252, s3, 17
	s_add_u32 s2, s24, 0x1eb00a00
	s_addc_u32 s3, s25, 0
	v_writelane_b32 v252, s2, 18
	v_mov_b64_e32 v[186:187], 0x200
	s_movk_i32 s33, 0x4c00
	v_writelane_b32 v252, s3, 19
	s_add_u32 s2, s24, 0x1eb00b00
	s_addc_u32 s3, s25, 0
	v_writelane_b32 v252, s2, 20
	s_mov_b32 s54, 0x800000
	s_movk_i32 s55, 0xfff
	v_writelane_b32 v252, s3, 21
	s_add_u32 s2, s24, 0x1eb00c00
	s_addc_u32 s3, s25, 0
	v_writelane_b32 v252, s2, 22
	s_movk_i32 s92, 0x1200
	s_mov_b32 s56, 0x3f317217
	v_writelane_b32 v252, s3, 23
	s_add_u32 s2, s24, 0x1eb00d00
	s_addc_u32 s3, s25, 0
	v_writelane_b32 v252, s2, 24
	s_mov_b32 s57, 0x7f800000
	s_movk_i32 s58, 0x210
	v_writelane_b32 v252, s3, 25
	s_add_u32 s2, s24, 0x1eb00e00
	s_addc_u32 s3, s25, 0
	v_writelane_b32 v252, s2, 26
	s_mov_b32 s59, 0xf800000
	s_mov_b32 s60, 0x42a00000
	v_writelane_b32 v252, s3, 27
	s_add_u32 s2, s24, 0x1eb00f00
	s_addc_u32 s3, s25, 0
	v_writelane_b32 v252, s2, 28
	s_movk_i32 s62, 0xa00
	s_mov_b64 s[34:35], 0x80
	v_writelane_b32 v252, s3, 29
	s_add_u32 s2, s24, 0x1eb01000
	s_addc_u32 s3, s25, 0
	v_writelane_b32 v252, s2, 30
	s_nop 1
	v_writelane_b32 v252, s3, 31
	s_add_u32 s2, s24, 0x1eb01100
	s_addc_u32 s3, s25, 0
	v_writelane_b32 v252, s2, 32
	s_nop 1
	v_writelane_b32 v252, s3, 33
	s_add_u32 s2, s24, 0x1eb01200
	s_addc_u32 s3, s25, 0
	v_writelane_b32 v252, s2, 34
	s_nop 1
	v_writelane_b32 v252, s3, 35
	s_add_u32 s2, s24, 0x1eb01300
	s_addc_u32 s3, s25, 0
	v_writelane_b32 v252, s2, 36
	s_cmp_eq_u32 s10, 15
	s_nop 0
	v_writelane_b32 v252, s3, 37
	s_cselect_b64 s[2:3], -1, 0
	v_writelane_b32 v252, s2, 38
	s_cmp_eq_u32 s10, 14
	s_nop 0
	v_writelane_b32 v252, s3, 39
	s_cselect_b64 s[2:3], -1, 0
	v_writelane_b32 v252, s2, 40
	s_cmp_eq_u32 s10, 13
	s_nop 0
	v_writelane_b32 v252, s3, 41
	s_cselect_b64 s[2:3], -1, 0
	v_writelane_b32 v252, s2, 42
	s_cmp_eq_u32 s10, 12
	s_nop 0
	v_writelane_b32 v252, s3, 43
	s_cselect_b64 s[2:3], -1, 0
	v_writelane_b32 v252, s2, 44
	s_cmp_eq_u32 s10, 11
	s_nop 0
	v_writelane_b32 v252, s3, 45
	s_cselect_b64 s[2:3], -1, 0
	v_writelane_b32 v252, s2, 46
	s_cmp_eq_u32 s10, 10
	s_nop 0
	v_writelane_b32 v252, s3, 47
	s_cselect_b64 s[2:3], -1, 0
	v_writelane_b32 v252, s2, 48
	s_cmp_eq_u32 s10, 9
	s_nop 0
	v_writelane_b32 v252, s3, 49
	s_cselect_b64 s[2:3], -1, 0
	v_writelane_b32 v252, s2, 50
	s_cmp_eq_u32 s10, 8
	s_nop 0
	v_writelane_b32 v252, s3, 51
	s_cselect_b64 s[2:3], -1, 0
	v_writelane_b32 v252, s2, 52
	s_cmp_eq_u32 s10, 7
	s_nop 0
	v_writelane_b32 v252, s3, 53
	s_cselect_b64 s[2:3], -1, 0
	v_writelane_b32 v252, s2, 54
	s_cmp_eq_u32 s10, 6
	s_nop 0
	v_writelane_b32 v252, s3, 55
	s_cselect_b64 s[2:3], -1, 0
	v_writelane_b32 v252, s2, 56
	s_cmp_eq_u32 s10, 5
	s_nop 0
	v_writelane_b32 v252, s3, 57
	s_cselect_b64 s[2:3], -1, 0
	v_writelane_b32 v252, s2, 58
	s_cmp_eq_u32 s10, 4
	s_nop 0
	v_writelane_b32 v252, s3, 59
	s_cselect_b64 s[2:3], -1, 0
	v_writelane_b32 v252, s2, 60
	s_cmp_eq_u32 s10, 3
	s_nop 0
	v_writelane_b32 v252, s3, 61
	s_cselect_b64 s[2:3], -1, 0
	v_writelane_b32 v252, s2, 62
	s_cmp_eq_u32 s10, 2
	s_nop 0
	v_writelane_b32 v252, s3, 63
	s_cselect_b64 s[2:3], -1, 0
	v_writelane_b32 v253, s2, 0
	s_cmp_eq_u32 s10, 1
	s_nop 0
	v_writelane_b32 v253, s3, 1
	s_cselect_b64 s[2:3], -1, 0
	v_writelane_b32 v253, s2, 2
	s_cmp_eq_u32 s10, 0
	s_nop 0
	v_writelane_b32 v253, s3, 3
	s_cselect_b64 s[2:3], -1, 0
	v_writelane_b32 v253, s2, 4
	s_nop 1
	v_writelane_b32 v253, s3, 5
	s_lshl_b32 s2, s9, 2
	s_add_u32 s0, s0, s2
	s_addc_u32 s1, s1, 0
	s_add_u32 s2, s0, 0x1400
	s_addc_u32 s3, s1, 0
	v_writelane_b32 v253, s2, 6
	s_add_u32 s0, s0, 0x2400
	s_addc_u32 s1, s1, 0
	v_writelane_b32 v253, s3, 7
	v_writelane_b32 v253, s0, 8
	s_nop 1
	v_writelane_b32 v253, s1, 9
	s_add_u32 s0, s24, 0x1eb03400
	s_addc_u32 s1, s25, 0
	v_writelane_b32 v253, s0, 10
	s_nop 1
	v_writelane_b32 v253, s1, 11
	s_add_u32 s0, s24, 0x1eb03500
	s_addc_u32 s1, s25, 0
	v_writelane_b32 v253, s0, 12
	s_cmpk_lt_i32 s90, 0x980
	s_cselect_b64 s[2:3], -1, 0
	v_writelane_b32 v253, s1, 13
	s_and_b32 s6, s90, 7
	s_lshl_b32 s6, s6, 5
	s_lshr_b32 s7, s90, 3
	s_add_i32 s6, s6, s7
	s_cmpk_lg_i32 s26, 0x100
	s_cselect_b32 s6, s90, s6
	s_mul_hi_i32 s0, s6, 0x2aaaaaab
	s_lshr_b32 s1, s0, 31
	s_ashr_i32 s0, s0, 6
	s_add_i32 s0, s0, s1
	s_mul_i32 s1, s0, 0x180
	v_writelane_b32 v253, s2, 14
	s_sub_i32 s1, s6, s1
	s_lshl_b32 s0, s0, 12
;     __device__ bool next(int i, Unit& u) const {
;         const long L = (long)i * G + c; if (L >= nwg) return false;
;         int wgid = (int)L; { const int q = nwg / NXCD, r = nwg % NXCD, xcd = wgid % NXCD, off = wgid / NXCD; wgid = (xcd < r ? xcd * (q + 1) : r * (q + 1) + (xcd - r) * q) + off; }
;         const int nig = WGM * nN, gid = wgid / nig, fm = gid * WGM, gsz = (nM - fm) < WGM ? (nM - fm) : WGM;
;         u.pm = fm + ((wgid % nig) % gsz); u.pn = (wgid % nig) / gsz; return true;
;     }
;     __device__ bool next(int i, Unit& u) const {
;         if (G == 256) {
;             const int k = i >> 2; if (k >= 2) return false;
;             const int r = c >> 3; u.pm = k * 64 + (c & 7) * 8 + (r >> 2); u.pn = (i & 3) * 4 + (r & 3); return true; }
;         const int su = (i >> 2) * G + c; if (su >= 512) return false;
;         u.pm = su >> 2; u.pn = (i & 3) * 4 + (su & 3); return true;
	v_writelane_b32 v253, s3, 15
	s_ashr_i32 s2, s1, 6
	s_and_b32 s7, s2, -2
	s_and_b32 s2, s1, 31
	s_sub_i32 s3, 5, s7
	s_lshr_b32 s3, s2, s3
	s_or_b32 s0, s3, s0
	s_ashr_i32 s91, s90, 31
	v_writelane_b32 v253, s0, 16
	s_lshr_b32 s0, s91, 29
	s_add_i32 s0, s90, s0
	s_ashr_i32 s3, s0, 3
	s_and_b32 s0, s0, -8
	s_sub_i32 s9, s90, s0
	s_lshl_b32 s0, s1, 1
	s_andn2_b32 s0, s0, 63
	s_lshr_b32 s6, 32, s7
	s_ashr_i32 s1, s0, 31
	s_add_i32 s6, s6, -1
	v_writelane_b32 v253, s0, 17
	s_and_b32 s6, s6, s2
	s_lshl_b32 s6, s6, 7
	v_writelane_b32 v253, s1, 18
	v_writelane_b32 v253, s7, 19
	s_lshr_b32 s0, 0x1000, s7
	s_mul_i32 s2, s27, s26
	s_ashr_i32 s27, s26, 31
	v_writelane_b32 v253, s0, 20
	s_sub_i32 s0, s6, 64
	v_writelane_b32 v253, s6, 21
	s_cmpk_lt_i32 s90, 0xc00
	v_writelane_b32 v253, s0, 22
	s_cselect_b64 s[0:1], -1, 0
	v_writelane_b32 v253, s0, 23
	s_cmpk_lt_i32 s90, 0x200
	s_cselect_b64 s[22:23], -1, 0
	v_writelane_b32 v253, s1, 24
	s_lshl_b32 s0, s90, 9
	v_writelane_b32 v253, s0, 25
	s_lshl_b32 s0, s26, 9
	v_writelane_b32 v253, s0, 26
	s_lshl_b32 s0, s90, 4
	s_cmpk_lt_i32 s90, 0x100
	v_writelane_b32 v253, s0, 27
	s_cselect_b64 s[0:1], -1, 0
	s_lshl_b32 s6, s9, 6
	v_writelane_b32 v253, s0, 28
	s_cmpk_lg_i32 s26, 0x100
	s_nop 0
	v_writelane_b32 v253, s1, 29
	s_cselect_b64 s[0:1], -1, 0
	v_writelane_b32 v253, s0, 30
	s_cmpk_gt_i32 s90, 0x1ff
	s_nop 0
	v_writelane_b32 v253, s1, 31
	s_cselect_b64 s[0:1], -1, 0
	s_and_b32 s7, s11, 56
	s_ashr_i32 s10, s90, 5
	s_add_i32 s21, s7, s10
	s_ashr_i32 s14, s90, 2
	s_lshr_b32 s15, s90, 3
	s_bfe_u32 s7, s90, 0x20003
	v_writelane_b32 v253, s11, 32
	s_cmpk_lt_i32 s90, 0xb00
	v_writelane_b32 v253, s7, 33
	s_cselect_b64 s[10:11], -1, 0
	s_cmp_lt_i32 s9, 0
	s_mul_i32 s7, s9, 0x41
	s_cselect_b32 s6, s7, s6
	s_movk_i32 s7, 0x131
	v_writelane_b32 v253, s10, 34
	s_cselect_b32 s7, s7, 0x130
	s_mul_i32 s7, s9, s7
	v_writelane_b32 v253, s11, 35
	s_movk_i32 s10, 0x161
	s_cselect_b32 s16, s10, 0x160
	s_add_i32 s7, s7, s3
	s_mul_hi_i32 s10, s7, 0x6bca1af3
	s_lshr_b32 s11, s10, 31
	s_ashr_i32 s10, s10, 6
	s_add_i32 s10, s10, s11
	s_mul_i32 s11, s10, 0x98
	s_sub_i32 s7, s7, s11
	s_bfe_u32 s11, s7, 0x3001c
	s_add_i32 s11, s7, s11
	s_and_b32 s12, s11, 0xfff8
	s_add_i32 s6, s6, s3
	s_sub_i32 s7, s7, s12
	s_ashr_i32 s12, s6, 31
	s_lshr_b32 s12, s12, 27
	s_add_i32 s12, s6, s12
	s_and_b32 s13, s12, 0xffe0
	s_sub_i32 s6, s6, s13
	s_bfe_i32 s13, s6, 0x80000
	s_bfe_u32 s13, s13, 0x3000c
	s_add_i32 s13, s6, s13
	s_and_b32 s17, s13, 0xf8
	s_sub_i32 s17, s6, s17
	s_lshl_b32 s6, s10, 3
	s_sext_i32_i16 s10, s11
	s_sext_i32_i16 s7, s7
	s_add_i32 s28, s6, s7
	s_ashr_i32 s6, s10, 3
	v_writelane_b32 v253, s6, 36
	s_lshr_b32 s6, s10, 3
	s_bfe_i64 s[6:7], s[6:7], 0x100000
	s_lshl_b64 s[6:7], s[6:7], 19
	v_writelane_b32 v253, s6, 37
	s_sext_i32_i8 s10, s17
	s_ashr_i32 s29, s28, 31
	v_writelane_b32 v253, s7, 38
	s_ashr_i32 s6, s12, 5
	s_bfe_i32 s7, s13, 0x80000
	s_lshl_b32 s6, s6, 3
	s_sext_i32_i16 s7, s7
	s_add_i32 s30, s6, s10
	s_ashr_i32 s6, s7, 3
	v_writelane_b32 v253, s6, 39
	s_mov_b32 s10, s28
	v_writelane_b32 v253, s10, 40
	s_ashr_i32 s31, s30, 31
	s_lshr_b32 s6, s7, 3
	v_writelane_b32 v253, s11, 41
	s_lshl_b64 s[10:11], s[28:29], 19
	v_writelane_b32 v253, s10, 42
	s_bfe_i64 s[6:7], s[6:7], 0x100000
	s_nop 0
	v_writelane_b32 v253, s11, 43
	s_lshl_b64 s[10:11], s[30:31], 17
	v_writelane_b32 v253, s10, 44
	s_nop 1
	v_writelane_b32 v253, s11, 45
	s_lshl_b64 s[10:11], s[6:7], 17
	v_writelane_b32 v253, s10, 46
	s_cmpk_eq_i32 s26, 0x100
	s_nop 0
	v_writelane_b32 v253, s11, 47
	s_cselect_b64 s[10:11], -1, 0
	s_and_b64 s[12:13], s[10:11], exec
	s_cselect_b32 s28, s21, s14
	s_or_b64 s[0:1], s[10:11], s[0:1]
	s_and_b64 s[0:1], s[0:1], exec
	s_mul_i32 s0, s9, s16
	s_cselect_b32 s1, s15, s90
	s_add_i32 s0, s0, s3
	s_mul_hi_i32 s3, s0, 0x2e8ba2e9
	s_lshr_b32 s9, s3, 31
	s_ashr_i32 s3, s3, 5
	s_add_i32 s3, s3, s9
	s_mul_i32 s9, s3, 0xb0
	s_sub_i32 s0, s0, s9
	s_bfe_u32 s9, s0, 0x3001c
	s_add_i32 s9, s0, s9
	s_and_b32 s12, s9, 0xfff8
	s_sub_i32 s0, s0, s12
	s_abs_i32 s12, s26
	v_cvt_f32_u32_e32 v1, s12
	v_writelane_b32 v253, s21, 48
	v_writelane_b32 v253, s22, 49
	s_sub_i32 s13, 0, s12
	v_rcp_iflag_f32_e32 v1, v1
	v_writelane_b32 v253, s23, 50
	s_or_b64 s[10:11], s[10:11], s[22:23]
	v_writelane_b32 v253, s10, 51
	v_mul_f32_e32 v1, 0x4f7ffffe, v1
	v_cvt_u32_f32_e32 v1, v1
	v_writelane_b32 v253, s11, 52
	s_lshl_b64 s[6:7], s[6:7], 19
	v_writelane_b32 v253, s6, 53
	v_readfirstlane_b32 s14, v1
	s_mul_i32 s13, s13, s14
;     __device__ __forceinline__ bf16_t* bfp(size_t off) const { return (bf16_t*)(ws + off); }
; #define FRESH() do { int _t = threadIdx.x; asm volatile("" : "+v"(_t)); C.tid = _t; C.lane = _t & 63; C.wave = __builtin_amdgcn_readfirstlane(_t >> 6); size_t _z = 0; asm volatile("" : "+s"(_z)); C.ws = prm.ws + _z; C.out = prm.out + _z; } while (0)
; #define GSYNC() do { xcd_barrier(xbar); FRESH(); } while (0)
; __global__ void __launch_bounds__(NTHR, 2) fwd_megakernel(Params prm) {
;     ...
;     const int G = C.G, bid = C.bid;
;     for (int l = 0; l < 2; ++l) {
;         const float* xin = (l == 0) ? C.P->in[0] : C.out;
;         FRESH();
;         for (int _m = 0; _m < REP_MIXC; ++_m) phase_p0(C, l, xin);
;         if (l == 0) { grid.sync(); FRESH(); } else GSYNC();
;         for (int _g = 0; _g < REP_GEMM; ++_g) { pg8::Gemm g{C.bfp(OFF_H), C.bfp(OFF_WIN), M_TOK, INW, 1024}; pg8::StaticOrder S; S.init(M_TOK, INW, G, bid);
;           pg8::EpiProj E{C.bfp(OFF_PROJA), C.bfp(OFF_PROJB), C.bfp(OFF_PROJC), C.bfp(OFF_PROJD)};
;           pg8::gemm_phase<pg8::EpiProj, pg8::StaticOrder, true, true>(ldsg, g, S, E); }
;         {
;             const int tc = 2432 % G; const bool all = (tc == 0);
;             if (all || bid >= tc) { FRESH(); const int nwk = all ? G : G - tc, idx = all ? bid : bid - tc;
	s_mul_hi_u32 s13, s14, s13
	s_add_i32 s14, s14, s13
	s_and_b32 s13, s1, 3
	s_lshl_b32 s1, s3, 3
	s_sext_i32_i16 s3, s9
	s_sext_i32_i16 s0, s0
	v_writelane_b32 v253, s7, 54
	s_add_i32 s10, s1, s0
	s_ashr_i32 s0, s3, 3
	v_writelane_b32 v253, s0, 55
	s_lshr_b32 s0, s3, 3
	s_bfe_i64 s[0:1], s[0:1], 0x100000
	s_lshl_b64 s[0:1], s[0:1], 19
	v_writelane_b32 v253, s0, 56
	s_mov_b32 s6, s28
	s_ashr_i32 s29, s28, 31
	v_writelane_b32 v253, s1, 57
	v_writelane_b32 v253, s13, 58
	s_lshl_b32 s1, s13, 19
	v_writelane_b32 v253, s1, 59
	v_writelane_b32 v253, s6, 60
	s_mul_hi_u32 s0, s14, 0x980
	s_mul_i32 s0, s0, s12
	v_writelane_b32 v253, s7, 61
	s_lshl_b64 s[6:7], s[28:29], 19
	v_writelane_b32 v253, s6, 62
	s_ashr_i32 s11, s10, 31
	s_sub_i32 s0, 0x980, s0
	v_writelane_b32 v253, s7, 63
	s_mov_b32 s6, s30
	v_writelane_b32 v254, s6, 0
	s_sub_i32 s1, s0, s12
	v_lshrrev_b32_e32 v1, 20, v0
	v_writelane_b32 v254, s7, 1
	s_lshl_b64 s[6:7], s[30:31], 19
	v_writelane_b32 v254, s6, 2
	v_lshrrev_b32_e32 v0, 10, v0
	v_or_b32_e32 v0, v0, v1
	v_writelane_b32 v254, s7, 3
	s_mov_b32 s6, s10
	v_writelane_b32 v254, s6, 4
	s_mov_b64 s[28:29], 0x180
	v_mbcnt_lo_u32_b32 v1, -1, 0
	v_writelane_b32 v254, s7, 5
	s_lshl_b64 s[6:7], s[10:11], 19
	s_cmp_ge_u32 s0, s12
	s_cselect_b32 s0, s1, s0
	s_sub_i32 s1, s0, s12
	s_cmp_ge_u32 s0, s12
	s_cselect_b32 s3, s1, s0
	s_cmp_eq_u32 s3, 0
	v_writelane_b32 v254, s6, 6
	s_cselect_b64 s[0:1], -1, 0
	s_cmp_ge_i32 s90, s3
	v_writelane_b32 v254, s7, 7
	s_cselect_b64 s[6:7], -1, 0
	s_or_b64 s[0:1], s[0:1], s[6:7]
	v_writelane_b32 v254, s0, 8
	s_ashr_i32 s21, s20, 31
	s_lshl_b64 s[40:41], s[20:21], 11
	v_writelane_b32 v254, s1, 9
	s_mul_i32 s0, s2, s8
	v_writelane_b32 v254, s0, 10
	s_movk_i32 s0, 0x3ff
	v_and_or_b32 v0, v0, s0, v224
	s_sub_i32 s0, s90, s3
	s_lshl_b32 s0, s0, 3
	v_writelane_b32 v254, s0, 11
	s_sub_i32 s0, s26, s3
	s_lshl_b32 s0, s0, 3
	v_writelane_b32 v254, s0, 12
	s_add_i32 s0, s26, s90
	v_writelane_b32 v254, s0, 13
	s_lshl_b32 s0, s0, 1
	v_writelane_b32 v254, s0, 14
	s_lshl_b32 s0, s26, 1
	v_writelane_b32 v254, s0, 15
	s_mov_b32 s0, s20
	v_writelane_b32 v254, s0, 16
	s_lshl_b64 s[52:53], s[18:19], 12
	v_mbcnt_hi_u32_b32 v221, -1, v1
	v_writelane_b32 v254, s1, 17
	s_lshl_b64 s[0:1], s[20:21], 12
	v_writelane_b32 v254, s0, 18
	s_movk_i32 s3, 0x84
	s_mov_b32 s2, 0x3c800000
	v_writelane_b32 v254, s1, 19
	s_mov_b32 s0, s18
	v_writelane_b32 v254, s0, 20
	s_mov_b32 s10, s37
	s_nop 0
	v_writelane_b32 v254, s1, 21
	s_lshl_b64 s[0:1], s[18:19], 11
	v_writelane_b32 v254, s0, 22
	s_nop 1
	v_writelane_b32 v254, s1, 23
	s_add_u32 s0, s24, 0xc001c00
	v_writelane_b32 v254, s0, 24
	s_addc_u32 s0, s25, 0
	v_writelane_b32 v254, s0, 25
	s_lshl_b32 s0, s90, 6
	v_writelane_b32 v254, s0, 26
	s_lshl_b32 s0, s26, 6
	v_writelane_b32 v254, s0, 27
	s_add_u32 s0, s24, 0x5000800
	v_writelane_b32 v254, s0, 28
	s_addc_u32 s0, s25, 0
	v_writelane_b32 v254, s0, 29
	s_add_u32 s0, s24, 0x1ebf4000
	v_writelane_b32 v254, s0, 30
	s_addc_u32 s0, s25, 0
	v_writelane_b32 v254, s0, 31
	s_lshl_b32 s0, s90, 12
	v_writelane_b32 v254, s0, 32
	s_lshl_b32 s0, s26, 12
	v_writelane_b32 v254, s0, 33
	s_add_i32 s0, 0, 0x26ff0
	v_writelane_b32 v254, s0, 34
	s_add_i32 s0, 0, 0x26ff4
	v_writelane_b32 v254, s0, 35
	s_add_i32 s0, 0, 0x16800
	v_writelane_b32 v254, s0, 36
	s_add_i32 s0, 0, 0x11000
	v_writelane_b32 v254, s0, 37
	s_add_i32 s0, 0, 0x8800
	v_writelane_b32 v254, s0, 38
	s_add_i32 s0, 0, 0xcc00
	v_writelane_b32 v254, s0, 39
	s_add_i32 s0, 0, 0x25090
	v_writelane_b32 v254, s0, 40
	s_add_i32 s0, 0, 0x250a0
	v_writelane_b32 v254, s0, 41
	s_add_i32 s0, 0, 0x250b0
	v_writelane_b32 v254, s0, 42
	s_add_i32 s0, 0, 0x250c0
	v_writelane_b32 v254, s0, 43
	s_add_i32 s0, 0, 0x250d0
	v_writelane_b32 v254, s0, 44
	s_add_i32 s0, 0, 0x250e0
	v_writelane_b32 v254, s0, 45
	s_add_i32 s0, 0, 0x250f0
	v_writelane_b32 v254, s0, 46
	v_cmp_eq_u32_e64 s[0:1], 0, v0
	s_add_i32 s61, 0, 0x25180
	s_add_i32 s63, 0, 0x25280
	v_writelane_b32 v254, s0, 47
	s_add_i32 s64, 0, 0x25380
	s_add_i32 s65, 0, 0x25480
	v_writelane_b32 v254, s1, 48
	s_lshl_b64 s[0:1], s[26:27], 15
	v_writelane_b32 v254, s0, 49
	s_nop 1
	v_writelane_b32 v254, s1, 50
	s_lshl_b64 s[0:1], s[26:27], 14
	v_writelane_b32 v254, s0, 51
	s_nop 1
	v_writelane_b32 v254, s1, 52
	v_writelane_b32 v254, s40, 53
	s_mov_b64 s[0:1], -1
	s_nop 0
	v_writelane_b32 v254, s41, 54
	v_writelane_b32 v254, s90, 55
	s_nop 1
	v_writelane_b32 v254, s91, 56
	v_writelane_b32 v254, s52, 57
	s_nop 1
	v_writelane_b32 v254, s53, 58
	s_branch .LBB0_8

;     __device__ __forceinline__ bf16_t* bfp(size_t off) const { return (bf16_t*)(ws + off); }
; __device__ __forceinline__ void attn_fetch(const Ctx& C, int it, u32x4 (&kv)[4], u32x4 (&vv)[4], u32x4 (&qv)[2]) {
;     ...
;     for (int k = 0; k < 2; ++k) { const int id = tid + NTHR * k, a = id >> 3, ch = id & 7;
;         qv[k] = *(const u32x4*)(pd + (size_t)(b * SEQ + r + dil * (128 * jb + a)) * 2304 + hq * 64 + ch * 8); }
; }
; __device__ __forceinline__ void attn_item(const Ctx& C, int it, int itn, u32x4 (&kv)[4], u32x4 (&vv)[4], u32x4 (&qv)[2]) {
;     const int tid = C.tid, lane = C.lane, w = C.wave;
;     const int b = it / 384, rem = it % 384, hq = rem >> 5, kk = rem & 31, g = hq >> 2, dil = 1 << (2 * g), n = SEQ / dil, nblk = 32 / dil, r = kk / nblk, jb = kk % nblk;
;     bf16_t* Ks = (bf16_t*)C.lds; bf16_t* Qs = Ks + 256 * 72; bf16_t* Vs = Qs + 128 * 72; float* bt = (float*)(Vs + 256 * 72);
;     bf16_t* pd = C.bfp(OFF_PROJD);
;     if (tid < 129) { const int rel = (tid - 64) * dil, na = rel < 0 ? -rel : rel;
;         int bk = na < 8 ? na : 8 + (na >= 15) + (na >= 27) + (na >= 50) + (na >= 91) + (na >= 166) + (na >= 305) + (na >= 559);
;         if (rel > 0) bk += 16;
;         bt[tid] = C.P->in[21][bk * 12 + hq]; }
;     ...
;     const int a = 16 * w + fr;
;     float mx = -1e30f;
; #pragma unroll
;     for (int kt = 0; kt < 9; ++kt)
; #pragma unroll
;         for (int rg = 0; rg < 4; ++rg) { const int cidx = 16 * (w + kt) + 4 * quad + rg, rel = cidx - 64 - a, ik = 128 * jb - 64 + cidx;
;             const bool valid = (rel >= -64) && (rel <= 64) && (ik >= 0) && (ik < n);
;             const int bi = rel < -64 ? 0 : (rel > 64 ? 128 : rel + 64);
;             const float s = valid ? sc[kt][rg] * 0.125f + bt[bi] : -1e30f;
;             sc[kt][rg] = s; mx = fmaxf(mx, s); }
.LBB0_342:
	s_or_b64 exec, exec, s[0:1]
	v_readlane_b32 s0, v253, 23
	v_readlane_b32 s1, v253, 24
	s_andn2_b64 vcc, exec, s[0:1]
	s_cbranch_vccnz .LBB0_433
	v_readlane_b32 s0, v253, 17
	v_readlane_b32 s1, v253, 18
	s_lshl_b64 s[0:1], s[0:1], 1
	v_readlane_b32 s7, v253, 21
	s_add_u32 s0, s42, s0
	v_readlane_b32 s4, v253, 19
	v_add_u32_e32 v34, s7, v93
	v_add_u32_e32 v36, s7, v92
	v_mov_b32_e32 v79, v65
	s_addc_u32 s1, s43, s1
	v_lshlrev_b32_e32 v34, s4, v34
	v_readlane_b32 s5, v253, 16
	v_lshlrev_b32_e32 v36, s4, v36
	v_lshl_add_u64 v[32:33], s[0:1], 0, v[78:79]
	v_add_u32_e32 v34, s5, v34
	s_movk_i32 s8, 0x1200
	v_add_u32_e32 v36, s5, v36
	v_mad_i64_i32 v[34:35], s[0:1], v34, s8, v[32:33]
	v_mad_i64_i32 v[36:37], s[0:1], v36, s8, v[32:33]
	global_load_dwordx4 v[32:35], v[34:35], off
	s_nop 0
	global_load_dwordx4 v[36:39], v[36:37], off
	s_movk_i32 s18, 0x81
	v_cmp_gt_i32_e64 s[0:1], s18, v40
	v_and_b32_e32 v43, 63, v40
	v_add_u32_e32 v42, 0, v78
	v_writelane_b32 v255, s0, 3
	s_movk_i32 s20, 0x90
	v_and_b32_e32 v45, 48, v40
	v_writelane_b32 v255, s1, 4
	v_cmp_lt_i32_e64 s[0:1], 64, v40
	v_and_b32_e32 v44, 15, v40
	v_readlane_b32 s21, v254, 36
	v_writelane_b32 v255, s0, 5
	v_and_b32_e32 v54, 64, v221
	v_add_u32_e32 v54, 64, v54
	v_writelane_b32 v255, s1, 6
	v_mad_u64_u32 v[82:83], s[0:1], v92, s20, v[42:43]
	v_mad_u64_u32 v[84:85], s[0:1], v93, s20, v[42:43]
	v_mad_u64_u32 v[86:87], s[0:1], v94, s20, v[42:43]
	v_mad_u64_u32 v[88:89], s[0:1], v95, s20, v[42:43]
	s_ashr_i32 s0, s6, 2
	s_nop 0
	v_bfi_b32 v83, -16, s0, v40
	s_and_b32 s1, s0, -16
	v_mul_lo_u32 v42, v83, s20
	v_add3_u32 v85, 0, v42, v45
	v_add_u32_e32 v45, 0, v45
	s_add_i32 s0, s1, 16
	v_add_u32_e32 v87, v45, v42
	v_or_b32_e32 v42, s0, v44
	s_add_i32 s4, s1, 32
	v_mul_lo_u32 v46, v42, s20
	v_or_b32_e32 v42, s4, v44
	s_add_i32 s5, s1, 48
	v_mul_lo_u32 v47, v42, s20
	v_or_b32_e32 v42, s5, v44
	s_add_i32 s6, s1, 64
	v_mul_lo_u32 v48, v42, s20
	v_or_b32_e32 v42, s6, v44
	s_add_i32 s7, s1, 0x50
	v_mul_lo_u32 v49, v42, s20
	v_or_b32_e32 v42, s7, v44
	s_add_i32 s8, s1, 0x60
	v_mul_lo_u32 v50, v42, s20
	v_or_b32_e32 v42, s8, v44
	s_add_i32 s9, s1, 0x70
	v_mul_lo_u32 v51, v42, s20
	v_or_b32_e32 v42, s9, v44
	s_add_i32 s12, s1, 0x80
	v_mul_lo_u32 v52, v42, s20
	v_or_b32_e32 v42, s12, v44
	v_mul_lo_u32 v53, v42, s20
	v_lshrrev_b32_e32 v42, 2, v40
	v_and_b32_e32 v42, 12, v42
	v_or_b32_e32 v89, s1, v42
	v_sub_u32_e32 v44, v42, v44
	v_cmp_gt_u32_e64 s[10:11], s18, v44
	v_or_b32_e32 v99, 1, v89
	v_lshl_add_u32 v98, v44, 2, s21
	v_writelane_b32 v255, s10, 7
	v_sub_u32_e32 v44, v99, v83
	v_or_b32_e32 v101, 2, v89
	v_writelane_b32 v255, s11, 8
	v_cmp_gt_u32_e64 s[10:11], s18, v44
	v_lshl_add_u32 v100, v44, 2, s21
	v_sub_u32_e32 v44, v101, v83
	v_writelane_b32 v255, s10, 9
	v_or_b32_e32 v103, 3, v89
	v_lshl_add_u32 v102, v44, 2, s21
	v_writelane_b32 v255, s11, 10
	v_cmp_gt_u32_e64 s[10:11], s18, v44
	v_sub_u32_e32 v44, v103, v83
	v_or_b32_e32 v105, s0, v42
	v_writelane_b32 v255, s10, 11
	v_lshl_add_u32 v104, v44, 2, s21
	v_or_b32_e32 v107, 1, v105
	v_writelane_b32 v255, s11, 12
	v_cmp_gt_u32_e64 s[10:11], s18, v44
	v_sub_u32_e32 v44, v105, v83
	v_cmp_gt_u32_e64 s[0:1], s18, v44
	v_writelane_b32 v255, s10, 13
	v_lshl_add_u32 v106, v44, 2, s21
	v_sub_u32_e32 v44, v107, v83
	v_writelane_b32 v255, s11, 14
	v_writelane_b32 v255, s0, 15
	v_or_b32_e32 v109, 2, v105
	v_lshl_add_u32 v108, v44, 2, s21
	v_writelane_b32 v255, s1, 16
	v_cmp_gt_u32_e64 s[0:1], s18, v44
	v_sub_u32_e32 v44, v109, v83
	v_or_b32_e32 v111, 3, v105
	v_writelane_b32 v255, s0, 17
	v_lshl_add_u32 v110, v44, 2, s21
	v_or_b32_e32 v113, s4, v42
	v_writelane_b32 v255, s1, 18
	v_cmp_gt_u32_e64 s[0:1], s18, v44
	v_sub_u32_e32 v44, v111, v83
	v_lshl_add_u32 v112, v44, 2, s21
	v_writelane_b32 v255, s0, 19
	v_or_b32_e32 v115, 1, v113
	v_or_b32_e32 v117, 2, v113
	v_writelane_b32 v255, s1, 20
	v_cmp_gt_u32_e64 s[0:1], s18, v44
	v_sub_u32_e32 v44, v113, v83
	v_lshl_add_u32 v114, v44, 2, s21
	v_writelane_b32 v255, s0, 21
	v_or_b32_e32 v119, 3, v113
	v_or_b32_e32 v121, s5, v42
	v_writelane_b32 v255, s1, 22
	v_cmp_gt_u32_e64 s[0:1], s18, v44
	v_sub_u32_e32 v44, v115, v83
	v_lshl_add_u32 v116, v44, 2, s21
	v_writelane_b32 v255, s0, 23
	v_or_b32_e32 v123, 1, v121
	v_or_b32_e32 v125, 2, v121
	v_writelane_b32 v255, s1, 24
	v_cmp_gt_u32_e64 s[0:1], s18, v44
	v_sub_u32_e32 v44, v117, v83
	v_lshl_add_u32 v118, v44, 2, s21
	v_writelane_b32 v255, s0, 25
	v_or_b32_e32 v127, 3, v121
	v_or_b32_e32 v129, s6, v42
	v_writelane_b32 v255, s1, 26
	v_cmp_gt_u32_e64 s[0:1], s18, v44
	v_sub_u32_e32 v44, v119, v83
	v_lshl_add_u32 v120, v44, 2, s21
	v_writelane_b32 v255, s0, 27
	v_or_b32_e32 v131, 1, v129
	v_or_b32_e32 v133, 2, v129
; __device__ __forceinline__ void attn_item(const Ctx& C, int it, int itn, u32x4 (&kv)[4], u32x4 (&vv)[4], u32x4 (&qv)[2]) {
;     ...
;     const int a = 16 * w + fr;
;     float mx = -1e30f;
; #pragma unroll
;     for (int kt = 0; kt < 9; ++kt)
; #pragma unroll
;         for (int rg = 0; rg < 4; ++rg) { const int cidx = 16 * (w + kt) + 4 * quad + rg, rel = cidx - 64 - a, ik = 128 * jb - 64 + cidx;
;             const bool valid = (rel >= -64) && (rel <= 64) && (ik >= 0) && (ik < n);
;             const int bi = rel < -64 ? 0 : (rel > 64 ? 128 : rel + 64);
;             const float s = valid ? sc[kt][rg] * 0.125f + bt[bi] : -1e30f;
;             sc[kt][rg] = s; mx = fmaxf(mx, s); }
; __global__ void __launch_bounds__(NTHR, 2) fwd_megakernel(Params prm) {
;     ...
;         { u32x4 akv[4], avv[4], aqv[2]; attn_fetch(C, bid, akv, avv, aqv);
;           for (int it = bid; it < 3072; it += G) attn_item(C, it, it + G, akv, avv, aqv); }
	v_writelane_b32 v255, s1, 28
	v_cmp_gt_u32_e64 s[0:1], s18, v44
	v_sub_u32_e32 v44, v121, v83
	v_lshl_add_u32 v122, v44, 2, s21
	v_writelane_b32 v255, s0, 29
	v_or_b32_e32 v135, 3, v129
	v_or_b32_e32 v137, s7, v42
	v_writelane_b32 v255, s1, 30
	v_cmp_gt_u32_e64 s[0:1], s18, v44
	v_sub_u32_e32 v44, v123, v83
	v_cmp_gt_u32_e64 s[22:23], s18, v44
	v_lshl_add_u32 v124, v44, 2, s21
	v_sub_u32_e32 v44, v125, v83
	v_writelane_b32 v255, s0, 31
	v_cmp_gt_u32_e64 s[30:31], s18, v44
	v_lshl_add_u32 v126, v44, 2, s21
	v_sub_u32_e32 v44, v127, v83
	v_writelane_b32 v255, s1, 32
	v_cmp_gt_u32_e64 s[0:1], s18, v44
	v_lshl_add_u32 v128, v44, 2, s21
	v_sub_u32_e32 v44, v129, v83
	v_writelane_b32 v255, s0, 33
	v_lshl_add_u32 v130, v44, 2, s21
	v_or_b32_e32 v139, 1, v137
	v_writelane_b32 v255, s1, 34
	v_cmp_gt_u32_e64 s[0:1], s18, v44
	v_sub_u32_e32 v44, v131, v83
	v_lshl_add_u32 v132, v44, 2, s21
	v_writelane_b32 v255, s0, 35
	v_or_b32_e32 v141, 2, v137
	v_or_b32_e32 v143, 3, v137
	v_writelane_b32 v255, s1, 36
	v_cmp_gt_u32_e64 s[0:1], s18, v44
	v_sub_u32_e32 v44, v133, v83
	v_lshl_add_u32 v134, v44, 2, s21
	v_writelane_b32 v255, s0, 37
	v_or_b32_e32 v145, s8, v42
	v_or_b32_e32 v147, 1, v145
	v_writelane_b32 v255, s1, 38
	v_cmp_gt_u32_e64 s[0:1], s18, v44
	v_sub_u32_e32 v44, v135, v83
	v_lshl_add_u32 v136, v44, 2, s21
	v_writelane_b32 v255, s0, 39
	v_or_b32_e32 v149, 2, v145
	v_or_b32_e32 v151, 3, v145
	v_writelane_b32 v255, s1, 40
	v_cmp_gt_u32_e64 s[0:1], s18, v44
	v_sub_u32_e32 v44, v137, v83
	v_cmp_gt_u32_e64 s[84:85], s18, v44
	v_lshl_add_u32 v138, v44, 2, s21
	v_sub_u32_e32 v44, v139, v83
	v_cmp_gt_u32_e64 s[86:87], s18, v44
	v_lshl_add_u32 v140, v44, 2, s21
	v_sub_u32_e32 v44, v141, v83
	v_cmp_gt_u32_e64 s[88:89], s18, v44
	v_lshl_add_u32 v142, v44, 2, s21
	v_sub_u32_e32 v44, v143, v83
	v_cmp_gt_u32_e64 s[90:91], s18, v44
	v_lshl_add_u32 v144, v44, 2, s21
	v_sub_u32_e32 v44, v145, v83
	v_cmp_gt_u32_e64 s[92:93], s18, v44
	v_lshl_add_u32 v146, v44, 2, s21
	v_sub_u32_e32 v44, v147, v83
	v_cmp_gt_u32_e64 s[94:95], s18, v44
	v_lshl_add_u32 v148, v44, 2, s21
	v_sub_u32_e32 v44, v149, v83
	v_cmp_gt_u32_e64 s[96:97], s18, v44
	v_lshl_add_u32 v150, v44, 2, s21
	v_sub_u32_e32 v44, v151, v83
	v_or_b32_e32 v153, s9, v42
	v_cmp_gt_u32_e64 s[38:39], s18, v44
	v_lshl_add_u32 v152, v44, 2, s21
	v_sub_u32_e32 v44, v153, v83
	v_or_b32_e32 v155, 1, v153
	v_cmp_gt_u32_e64 s[4:5], s18, v44
	v_lshl_add_u32 v154, v44, 2, s21
	v_sub_u32_e32 v44, v155, v83
	v_or_b32_e32 v157, 2, v153
	v_cmp_gt_u32_e64 s[6:7], s18, v44
	v_lshl_add_u32 v156, v44, 2, s21
	v_sub_u32_e32 v44, v157, v83
	v_or_b32_e32 v159, 3, v153
	v_cmp_gt_u32_e64 s[8:9], s18, v44
	v_lshl_add_u32 v158, v44, 2, s21
	v_sub_u32_e32 v44, v159, v83
	v_or_b32_e32 v161, s12, v42
	v_cmp_gt_u32_e64 s[10:11], s18, v44
	v_lshl_add_u32 v160, v44, 2, s21
	v_sub_u32_e32 v44, v161, v83
	v_or_b32_e32 v163, 1, v161
	v_cmp_gt_u32_e64 s[12:13], s18, v44
	v_lshl_add_u32 v162, v44, 2, s21
	v_sub_u32_e32 v44, v163, v83
	v_or_b32_e32 v165, 2, v161
	v_cmp_gt_u32_e64 s[14:15], s18, v44
	v_lshl_add_u32 v164, v44, 2, s21
	v_sub_u32_e32 v44, v165, v83
	v_or_b32_e32 v167, 3, v161
	v_cmp_gt_u32_e64 s[16:17], s18, v44
	v_lshl_add_u32 v166, v44, 2, s21
	v_sub_u32_e32 v44, v167, v83
	v_cmp_gt_u32_e64 s[18:19], s18, v44
	v_lshl_add_u32 v168, v44, 2, s21
	v_xor_b32_e32 v44, 16, v221
	v_cmp_lt_i32_e32 vcc, v44, v54
	v_subrev_u32_e32 v96, 64, v40
	v_lshl_add_u32 v97, v40, 2, s21
	v_writelane_b32 v255, s0, 41
	v_cndmask_b32_e32 v44, v221, v44, vcc
	v_bfe_u32 v40, v40, 2, 2
	v_writelane_b32 v255, s1, 42
	v_lshlrev_b32_e32 v169, 2, v44
	v_xor_b32_e32 v44, 32, v221
	v_or_b32_e32 v40, v89, v40
	s_add_u32 s0, s36, 0x1a000000
	v_cmp_lt_i32_e32 vcc, v44, v54
	v_mul_lo_u32 v40, v40, s20
	v_and_b32_e32 v41, 24, v41
	v_writelane_b32 v255, s0, 43
	s_addc_u32 s0, s40, 0
	v_cndmask_b32_e32 v44, v221, v44, vcc
	v_add3_u32 v171, 0, v40, v41
	v_writelane_b32 v255, s0, 44
	v_readlane_b32 s0, v254, 55
	v_lshl_add_u64 v[80:81], s[42:43], 0, v[78:79]
	s_movk_i32 s66, 0x1200
	v_lshlrev_b32_e32 v170, 2, v44
	v_add_u32_e32 v172, 0xd800, v171
	v_cmp_gt_u32_e64 s[20:21], 16, v43
	v_add_u32_e32 v173, v45, v46
	v_add_u32_e32 v174, v45, v47
	v_add_u32_e32 v175, v45, v48
	v_add_u32_e32 v176, v45, v49
	v_add_u32_e32 v177, v45, v50
	v_add_u32_e32 v183, v45, v51
	v_add_u32_e32 v192, v45, v52
	v_add_u32_e32 v193, v45, v53
	v_lshlrev_b32_e32 v90, 1, v42
	v_readlane_b32 s67, v254, 14
	s_mov_b32 s50, s0
	s_cmpk_lg_i32 s26, 0x100
	s_cbranch_scc1 .Lmy_attn_keep
	s_and_b32 s50, s0, 7
	s_lshl_b32 s50, s50, 5
	s_lshr_b32 s0, s0, 3
	s_add_i32 s50, s50, s0
	s_add_i32 s67, s50, s26
	s_lshl_b32 s67, s67, 1
.Lmy_attn_keep:
	v_readlane_b32 s1, v254, 56
	s_branch .LBB0_345
